# v7 + XCD-local grid-barrier seams between consecutive GEMM phases (leader skips L2 writeback and cross-XCD rendezvous when producers/consumers share an XCD; guarded by a runtime placement check)
# speedup vs baseline: 1.0207x; 1.0207x over previous
_ZN2mk10fwd_kernelENS_4ArgsE:
	s_load_dwordx4 s[80:83], s[0:1], 0x98
	s_mov_b32 s28, s2
	s_add_u32 s2, s0, 0xa8
	s_addc_u32 s3, s1, 0
	v_and_b32_e32 v218, 0x3ff, v0
	v_writelane_b32 v254, s2, 0
	v_cmp_gt_u32_e32 vcc, 16, v218
	s_nop 0
	v_writelane_b32 v254, s3, 1
	s_and_saveexec_b64 s[2:3], vcc
	v_lshl_add_u32 v1, v218, 2, 0
	v_add_u32_e32 v1, 0x24000, v1
	v_mov_b32_e32 v2, 0
	ds_write_b32 v1, v2
	s_or_b64 exec, exec, s[2:3]
	s_waitcnt lgkmcnt(0)
	s_barrier
	s_add_u32 s2, s80, 0x7c0000
	s_getreg_b32 s4, hwreg(HW_REG_XCC_ID, 0, 4)
	s_addc_u32 s3, s81, 0
	s_and_b32 s8, s4, 15
	v_cmp_eq_u32_e64 s[6:7], 0, v218
	s_mov_b64 s[4:5], exec
	s_nop 0
	v_writelane_b32 v254, s6, 2
	s_nop 1
	v_writelane_b32 v254, s7, 3
	s_and_b64 s[6:7], s[4:5], s[6:7]
	s_mov_b64 exec, s[6:7]
	s_cbranch_execz .LBB0_5
	s_mov_b64 s[6:7], exec
	v_mbcnt_lo_u32_b32 v1, s6, 0
	v_mbcnt_hi_u32_b32 v1, s7, v1
	v_cmp_eq_u32_e32 vcc, 0, v1
	s_and_b64 s[10:11], exec, vcc
	s_mov_b64 exec, s[10:11]
	s_cbranch_execz .LBB0_5
	s_and_b32 s10, s28, 7
	s_cmp_lg_u32 s10, s8
	s_cbranch_scc0 .Lxb_placed
	v_mov_b32_e32 v1, 0
	v_mov_b32_e32 v2, 1
	global_atomic_add v1, v2, s[2:3] offset:768
	s_waitcnt vmcnt(0)
.Lxb_placed:
	s_lshl_b32 s9, s8, 8
	s_bcnt1_i32_b64 s6, s[6:7]
	v_mov_b32_e32 v1, s9
	v_mov_b32_e32 v2, s6
	global_atomic_add v1, v2, s[2:3] offset:1024

.LBB0_568:
	v_readlane_b32 s2, v254, 28
	v_readlane_b32 s3, v254, 29
	global_load_dword v2, v161, s[34:35] sc1
	global_load_dword v17, v161, s[30:31] offset:256 sc1
	s_waitcnt lgkmcnt(0)
	global_load_dword v0, v161, s[26:27] sc1
	global_load_dword v1, v161, s[24:25] sc1
	s_mov_b64 s[4:5], -1
	s_waitcnt vmcnt(1)
	v_add_u32_e32 v16, v0, v2
	global_load_dword v3, v161, s[2:3] sc1
	v_readlane_b32 s2, v254, 30
	v_readlane_b32 s3, v254, 31
	s_waitcnt vmcnt(1)
	v_add_u32_e32 v16, v16, v1
	s_waitcnt vmcnt(0)
	v_add_u32_e32 v16, v16, v3
	s_nop 0
	global_load_dword v4, v161, s[2:3] sc1
	v_readlane_b32 s2, v254, 32
	v_readlane_b32 s3, v254, 33
	s_waitcnt vmcnt(0)
	v_add_u32_e32 v16, v16, v4
	s_nop 2
	global_load_dword v5, v161, s[2:3] sc1
	v_readlane_b32 s2, v254, 34
	v_readlane_b32 s3, v254, 35
	s_waitcnt vmcnt(0)
	v_add_u32_e32 v16, v16, v5
	s_nop 2
	global_load_dword v6, v161, s[2:3] sc1
	v_readlane_b32 s2, v254, 36
	v_readlane_b32 s3, v254, 37
	s_waitcnt vmcnt(0)
	v_add_u32_e32 v16, v16, v6
	s_nop 2
	global_load_dword v7, v161, s[2:3] sc1
	v_readlane_b32 s2, v254, 38
	v_readlane_b32 s3, v254, 39
	s_waitcnt vmcnt(0)
	v_add_u32_e32 v16, v16, v7
	s_nop 2
	global_load_dword v8, v161, s[2:3] sc1
	v_readlane_b32 s2, v254, 40
	v_readlane_b32 s3, v254, 41
	s_waitcnt vmcnt(0)
	v_add_u32_e32 v16, v16, v8
	s_nop 2
	global_load_dword v9, v161, s[2:3] sc1
	v_readlane_b32 s2, v254, 42
	v_readlane_b32 s3, v254, 43
	s_waitcnt vmcnt(0)
	v_add_u32_e32 v16, v16, v9
	s_nop 2
	global_load_dword v10, v161, s[2:3] sc1
	v_readlane_b32 s2, v254, 44
	v_readlane_b32 s3, v254, 45
	s_waitcnt vmcnt(0)
	v_add_u32_e32 v16, v16, v10
	s_nop 2
	global_load_dword v11, v161, s[2:3] sc1
	v_readlane_b32 s2, v254, 46
	v_readlane_b32 s3, v254, 47
	s_waitcnt vmcnt(0)
	v_add_u32_e32 v16, v16, v11
	s_nop 2
	global_load_dword v12, v161, s[2:3] sc1
	v_readlane_b32 s2, v254, 48
	v_readlane_b32 s3, v254, 49
	s_waitcnt vmcnt(0)
	v_add_u32_e32 v16, v16, v12
	s_nop 2
	global_load_dword v13, v161, s[2:3] sc1
	v_readlane_b32 s2, v254, 50
	v_readlane_b32 s3, v254, 51
	s_waitcnt vmcnt(0)
	v_add_u32_e32 v16, v16, v13
	s_nop 2
	global_load_dword v14, v161, s[2:3] sc1
	v_readlane_b32 s2, v254, 52
	v_readlane_b32 s3, v254, 53
	s_waitcnt vmcnt(0)
	v_add_u32_e32 v16, v16, v14
	s_nop 2
	global_load_dword v15, v161, s[2:3] sc1
	s_mov_b64 s[2:3], -1
	s_waitcnt vmcnt(0)
	v_add_u32_e32 v16, v16, v15
	v_cmp_eq_u32_e32 vcc, s29, v16
	s_cbranch_vccnz .LBB0_567
	s_and_b32 s2, s9, 0xff
	s_cmp_eq_u32 s2, 0
	s_mov_b64 s[2:3], -1
	s_mov_b64 s[6:7], -1
	s_sleep 1
	s_cbranch_scc0 .LBB0_572
	global_load_dword v16, v161, s[30:31] sc1
	s_waitcnt vmcnt(0)
	v_cmp_eq_u32_e32 vcc, 0, v16
	s_cbranch_vccnz .LBB0_574
	s_mov_b64 s[6:7], 0

.LBB0_579:
	v_readfirstlane_b32 s4, v17
	s_nop 1
	v_writelane_b32 v255, s4, 60
	v_readlane_b32 s2, v255, 20
	v_readlane_b32 s3, v255, 21
	v_cmp_ne_u32_e32 vcc, 0, v2
	s_nop 0
	v_cndmask_b32_e64 v16, 0, v2, s[2:3]
	v_readlane_b32 s2, v255, 18
	v_readlane_b32 s3, v255, 19
	v_cndmask_b32_e64 v2, 0, 1, vcc
	v_cmp_ne_u32_e32 vcc, 0, v0
	v_cndmask_b32_e64 v16, v16, v0, s[2:3]
	v_readlane_b32 s2, v255, 16
	v_readlane_b32 s3, v255, 17
	v_addc_co_u32_e32 v0, vcc, 0, v2, vcc
	s_nop 0
	v_cndmask_b32_e64 v16, v16, v1, s[2:3]
	v_readlane_b32 s2, v255, 14
	v_readlane_b32 s3, v255, 15
	v_cmp_ne_u32_e32 vcc, 0, v1
	s_nop 0
	v_cndmask_b32_e64 v16, v16, v3, s[2:3]
	v_readlane_b32 s2, v255, 12
	v_readlane_b32 s3, v255, 13
	v_cndmask_b32_e64 v1, 0, 1, vcc
	v_cmp_ne_u32_e32 vcc, 0, v3
	v_cndmask_b32_e64 v16, v16, v4, s[2:3]
	v_readlane_b32 s2, v255, 10
	v_readlane_b32 s3, v255, 11
	v_addc_co_u32_e32 v0, vcc, v0, v1, vcc
	s_nop 0
	v_cndmask_b32_e64 v16, v16, v5, s[2:3]
	v_readlane_b32 s2, v255, 8
	v_readlane_b32 s3, v255, 9
	v_cmp_ne_u32_e32 vcc, 0, v4
	s_nop 0
	v_cndmask_b32_e64 v16, v16, v6, s[2:3]
	v_readlane_b32 s2, v255, 6
	v_readlane_b32 s3, v255, 7
	v_cndmask_b32_e64 v1, 0, 1, vcc
	v_cmp_ne_u32_e32 vcc, 0, v5
	v_cndmask_b32_e64 v16, v16, v7, s[2:3]
	v_readlane_b32 s2, v255, 4
	v_readlane_b32 s3, v255, 5
	v_addc_co_u32_e32 v0, vcc, v0, v1, vcc
	s_nop 0
	v_cndmask_b32_e64 v16, v16, v8, s[2:3]
	v_readlane_b32 s2, v255, 2
	v_readlane_b32 s3, v255, 3
	v_cmp_ne_u32_e32 vcc, 0, v6
	s_nop 0
	v_cndmask_b32_e64 v16, v16, v9, s[2:3]
	v_readlane_b32 s2, v255, 0
	v_cndmask_b32_e64 v1, 0, 1, vcc
	v_cmp_ne_u32_e32 vcc, 0, v7
	v_readlane_b32 s3, v255, 1
	s_nop 0
	v_addc_co_u32_e32 v0, vcc, v0, v1, vcc
	v_cndmask_b32_e64 v16, v16, v10, s[2:3]
	v_readlane_b32 s2, v254, 62
	v_cmp_ne_u32_e32 vcc, 0, v8
	v_readlane_b32 s3, v254, 63
	s_nop 0
	v_cndmask_b32_e64 v1, 0, 1, vcc
	v_cmp_ne_u32_e32 vcc, 0, v9
	v_cndmask_b32_e64 v16, v16, v11, s[2:3]
	v_readlane_b32 s2, v254, 60
	v_addc_co_u32_e32 v0, vcc, v0, v1, vcc
	v_readlane_b32 s3, v254, 61
	v_cmp_ne_u32_e32 vcc, 0, v10
	s_nop 0
	v_cndmask_b32_e64 v16, v16, v12, s[2:3]
	v_readlane_b32 s2, v254, 58
	v_cndmask_b32_e64 v1, 0, 1, vcc
	v_cmp_ne_u32_e32 vcc, 0, v11
	v_readlane_b32 s3, v254, 59
	s_nop 0
	v_addc_co_u32_e32 v0, vcc, v0, v1, vcc
	v_cndmask_b32_e64 v16, v16, v13, s[2:3]
	v_readlane_b32 s2, v254, 56
	v_cmp_ne_u32_e32 vcc, 0, v12
	v_readlane_b32 s3, v254, 57
	s_nop 0
	v_cndmask_b32_e64 v1, 0, 1, vcc
	v_cmp_ne_u32_e32 vcc, 0, v13
	v_cndmask_b32_e64 v16, v16, v14, s[2:3]
	v_readlane_b32 s2, v254, 54
	v_addc_co_u32_e32 v0, vcc, v0, v1, vcc
	v_readlane_b32 s3, v254, 55
	v_cmp_ne_u32_e32 vcc, 0, v14
	s_nop 0
	v_cndmask_b32_e64 v16, v16, v15, s[2:3]
	v_cndmask_b32_e64 v1, 0, 1, vcc
	v_cmp_ne_u32_e32 vcc, 0, v15
	v_max_u32_e32 v2, 1, v16
	v_readlane_b32 s2, v255, 30
	v_addc_co_u32_e32 v0, vcc, v0, v1, vcc
	v_mov_b32_e32 v1, s8
	v_max_u32_e32 v0, 1, v0
	ds_write_b32 v1, v2
	v_mov_b32_e32 v1, s2
	ds_write_b32 v1, v0

.LBB0_596:
	s_andn2_saveexec_b64 s[2:3], s[2:3]
	s_cbranch_execz .LBB0_616
	s_mov_b32 s4, 0x19f0c
	s_bitcmp1_b32 s4, s82
	s_cbranch_scc0 .Lxb_global
	v_readlane_b32 s4, v255, 60
	s_nop 3
	s_cmp_eq_u32 s4, 0
	s_cbranch_scc1 .Lxb_local
.Lxb_global:
	s_mov_b64 s[2:3], exec
	buffer_wbl2 sc1
	s_waitcnt lgkmcnt(0)
	s_waitcnt vmcnt(0)
	v_mbcnt_lo_u32_b32 v1, s2, 0
	v_mbcnt_hi_u32_b32 v1, s3, v1
	v_cmp_eq_u32_e32 vcc, 0, v1
	s_and_saveexec_b64 s[4:5], vcc
	s_cbranch_execz .LBB0_599
	s_bcnt1_i32_b64 s2, s[2:3]
	v_mov_b32_e32 v2, s2
	v_readlane_b32 s2, v255, 26
	v_readlane_b32 s3, v255, 27
	s_nop 4
	global_atomic_add v2, v161, v2, s[2:3] sc0

.Lxb_local:
	s_mov_b64 s[2:3], exec
	v_mbcnt_lo_u32_b32 v0, s2, 0
	v_mbcnt_hi_u32_b32 v0, s3, v0
	v_cmp_eq_u32_e32 vcc, 0, v0
	s_waitcnt vmcnt(0)
	buffer_inv sc1
	s_and_saveexec_b64 s[4:5], vcc
	s_cbranch_execz .LBB0_615
	s_bcnt1_i32_b64 s2, s[2:3]
	v_mov_b32_e32 v0, s2
	v_readlane_b32 s2, v255, 24
	v_readlane_b32 s3, v255, 25
	s_nop 4
	global_atomic_add v161, v0, s[2:3]
